# v42 with P2/P10 column tiles in descending order (no per-group rotation): newest-written activation columns are read first by the FFN-out phases
# baseline (speedup 1.0000x reference)
.LBB0_227:
	s_cmp_lt_i32 s76, 3
	s_cselect_b64 s[0:1], -1, 0
	s_add_u32 s80, s74, 0x5800000
	s_addc_u32 s81, s75, 0
	s_and_b64 s[0:1], s[0:1], s[2:3]
	s_andn2_b64 vcc, exec, s[0:1]
	s_cbranch_vccnz .LBB0_249
	s_cmpk_gt_i32 s96, 0x5d7
	v_readfirstlane_b32 s3, v236
	s_cbranch_scc1 .LBB0_244
	v_lshrrev_b32_e32 v0, 5, v236
	v_lshrrev_b32_e32 v2, 1, v236
	v_and_b32_e32 v0, 4, v0
	v_bfe_u32 v1, v236, 2, 2
	v_and_b32_e32 v11, 24, v2
	v_or3_b32 v0, v0, v1, v11
	v_lshlrev_b32_e32 v1, 4, v236
	v_add_u32_e32 v8, 0x2000, v1
	v_lshrrev_b32_e32 v2, 7, v8
	s_movk_i32 s2, 0xe0
	v_and_b32_e32 v4, 32, v236
	v_and_or_b32 v3, v2, s2, v0
	v_bitop3_b32 v9, v1, v4, 48 bitop3:0x6c
	v_and_b32_e32 v10, 64, v236
	v_bfe_u32 v12, v236, 2, 4
	s_movk_i32 s2, 0xf0
	v_or_b32_e32 v1, v9, v10
	v_and_or_b32 v2, v2, s2, v12
	s_add_u32 s26, s74, 0x100000
	v_lshl_or_b32 v130, v2, 11, v1
	v_lshrrev_b32_e32 v2, 3, v236
	s_movk_i32 s2, 0x60
	s_addc_u32 s27, s75, 0
	v_and_or_b32 v0, v2, s2, v0
	s_movk_i32 s2, 0x70
	s_ashr_i32 s29, s96, 31
	v_lshl_or_b32 v132, v0, 11, v1
	v_and_or_b32 v0, v2, s2, v12
	s_lshr_b32 s2, s29, 29
	s_add_i32 s2, s96, s2
	s_lshr_b32 s6, s3, 6
	s_ashr_i32 s4, s2, 3
	s_and_b32 s2, s2, -8
	s_lshr_b32 s8, s3, 8
	s_lshl_b32 s28, s6, 10
	s_sub_i32 s2, s96, s2
	s_cmp_lt_i32 s2, 0
	s_movk_i32 s30, 0xbc
	s_cselect_b32 s5, s30, 0xbb
	s_mul_i32 s2, s2, s5
	s_add_i32 s2, s2, s4
	s_mul_hi_i32 s4, s2, 0x2e8ba2e9
	s_lshr_b32 s5, s4, 31
	s_ashr_i32 s4, s4, 5
	s_add_i32 s4, s4, s5
	s_lshl_b32 s7, s4, 3
	s_sub_i32 s5, 0x44, s7
	s_mulk_i32 s4, 0xb0
	s_min_u32 s9, s5, 8
	s_sub_i32 s10, s2, s4
	v_lshl_or_b32 v128, v3, 11, v1
	s_sext_i32_i16 s2, s10
	v_cvt_f32_ubyte0_e32 v3, s9
	v_cvt_f32_i32_e32 v2, s2
	v_rcp_iflag_f32_e32 v4, v3
	v_lshl_or_b32 v134, v0, 11, v1
	s_ashr_i32 s2, s2, 30
	s_or_b32 s2, s2, 1
	v_mul_f32_e32 v0, v2, v4
	v_trunc_f32_e32 v0, v0
	v_fma_f32 v1, -v0, v3, v2
	v_cvt_i32_f32_e32 v0, v0
	v_cmp_ge_f32_e64 s[4:5], |v1|, v3
	s_and_b64 s[4:5], s[4:5], exec
	s_cselect_b32 s2, s2, 0
	v_readfirstlane_b32 s4, v0
	s_add_i32 s2, s4, s2
	s_mul_i32 s4, s2, s9
	s_sub_i32 s4, s10, s4
	s_sext_i32_i16 s4, s4
	s_add_i32 s18, s7, s4
	s_sub_i32 s2, 21, s2
	s_ashr_i32 s19, s18, 31
	s_bfe_i64 s[10:11], s[2:3], 0x100000
	s_lshl_b64 s[4:5], s[18:19], 19
	s_lshl_b64 s[10:11], s[10:11], 19
	s_add_u32 s22, s26, s10
	s_addc_u32 s23, s27, s11
	s_add_i32 s19, s28, 0
	s_add_i32 m0, s19, 0x10000
	v_mov_b32_e32 v133, 0
	global_load_lds_dwordx4 v132, s[22:23]
	s_add_i32 m0, s19, 0x12000
	s_add_u32 s10, s22, 0x40000
	global_load_lds_dwordx4 v128, s[22:23]
	s_addc_u32 s11, s23, 0
	s_add_i32 m0, s19, 0x14000
	v_mov_b32_e32 v129, v133
	global_load_lds_dwordx4 v132, s[10:11]
	s_add_i32 m0, s19, 0x16000
	v_mov_b32_e32 v135, v133
	global_load_lds_dwordx4 v128, s[10:11]
	v_readlane_b32 s10, v246, 42
	v_readlane_b32 s11, v246, 43
	s_add_u32 s20, s10, s4
	s_addc_u32 s21, s11, s5
	s_add_i32 s31, s19, 0x2000
	s_mov_b32 m0, s19
	s_add_u32 s4, s20, 0x40000
	global_load_lds_dwordx4 v134, s[20:21]
	s_mov_b32 m0, s31
	s_addc_u32 s5, s21, 0
	s_add_i32 s33, s19, 0x4000
	global_load_lds_dwordx4 v130, s[20:21]
	s_mov_b32 m0, s33
	s_add_i32 s34, s19, 0x6000
	global_load_lds_dwordx4 v134, s[4:5]
	s_mov_b32 m0, s34
	v_mov_b32_e32 v131, v133
	global_load_lds_dwordx4 v130, s[4:5]
	s_cmp_eq_u32 s8, 1
	s_mov_b32 s35, 0
	v_lshl_add_u64 v[6:7], s[22:23], 0, v[132:133]
	v_lshl_add_u64 v[4:5], s[22:23], 0, v[128:129]
	v_lshl_add_u64 v[0:1], s[20:21], 0, v[134:135]
	s_cselect_b64 s[4:5], -1, 0
	s_cmp_lg_u32 s8, 1
	v_lshl_add_u64 v[2:3], s[20:21], 0, v[130:131]
	s_cbranch_scc1 .LBB0_231
	s_barrier

.LBB0_234:
	s_add_i32 s35, s35, 1
	s_mul_i32 s2, s35, s38
	s_mul_hi_u32 s3, s35, s39
	s_add_i32 s3, s3, s2
	s_mul_i32 s2, s35, s39
	s_add_u32 s14, s2, s96
	s_addc_u32 s15, s3, s29
	v_cmp_gt_i64_e32 vcc, s[14:15], v[142:143]
	v_cmp_lt_i64_e64 s[2:3], s[14:15], v[140:141]
	s_cbranch_vccnz .LBB0_236
	s_ashr_i32 s10, s14, 31
	s_lshr_b32 s10, s10, 29
	s_add_i32 s10, s14, s10
	s_ashr_i32 s11, s10, 3
	s_and_b32 s10, s10, -8
	s_sub_i32 s10, s14, s10
	s_cmp_lt_i32 s10, 0
	s_cselect_b32 s12, s30, 0xbb
	s_mul_i32 s10, s10, s12
	s_add_i32 s10, s10, s11
	s_mul_hi_i32 s11, s10, 0x2e8ba2e9
	s_lshr_b32 s12, s11, 31
	s_ashr_i32 s11, s11, 5
	s_add_i32 s11, s11, s12
	s_lshl_b32 s12, s11, 3
	s_sub_i32 s13, 0x44, s12
	s_min_i32 s13, s13, 8
	s_abs_i32 s14, s13
	v_cvt_f32_u32_e32 v0, s14
	s_sub_i32 s16, 0, s14
	s_mulk_i32 s11, 0xb0
	s_sub_i32 s11, s10, s11
	v_rcp_iflag_f32_e32 v0, v0
	s_abs_i32 s10, s11
	s_xor_b32 s15, s11, s13
	s_ashr_i32 s15, s15, 31
	v_mul_f32_e32 v0, 0x4f7ffffe, v0
	v_cvt_u32_f32_e32 v0, v0
	s_nop 0
	v_readfirstlane_b32 s17, v0
	s_mul_i32 s16, s16, s17
	s_mul_hi_u32 s16, s17, s16
	s_add_i32 s17, s17, s16
	s_mul_hi_u32 s16, s10, s17
	s_mul_i32 s17, s16, s14
	s_sub_i32 s10, s10, s17
	s_add_i32 s24, s16, 1
	s_sub_i32 s17, s10, s14
	s_cmp_ge_u32 s10, s14
	s_cselect_b32 s16, s24, s16
	s_cselect_b32 s10, s17, s10
	s_add_i32 s17, s16, 1
	s_cmp_ge_u32 s10, s14
	s_cselect_b32 s10, s17, s16
	s_xor_b32 s10, s10, s15
	s_sub_i32 s10, s10, s15
	s_mul_i32 s13, s10, s13
	s_sub_i32 s11, s11, s13
	s_add_i32 s12, s12, s11
	s_sub_i32 s10, 21, s10

.LBB0_1209:
	s_cmp_lt_i32 s76, 11
	s_cselect_b64 s[2:3], -1, 0
	s_and_b64 s[0:1], s[2:3], s[0:1]
	s_andn2_b64 vcc, exec, s[0:1]
	s_cbranch_vccnz .LBB0_1243
	s_add_u32 s4, s74, 0x2500000
	s_addc_u32 s5, s75, 0
	v_readlane_b32 s9, v246, 46
	s_cmpk_gt_i32 s9, 0x5d7
	v_readfirstlane_b32 s3, v236
	s_cbranch_scc1 .LBB0_1226
	v_lshrrev_b32_e32 v0, 5, v236
	v_lshrrev_b32_e32 v2, 1, v236
	v_and_b32_e32 v0, 4, v0
	v_bfe_u32 v1, v236, 2, 2
	v_and_b32_e32 v11, 24, v2
	v_or3_b32 v0, v0, v1, v11
	v_lshlrev_b32_e32 v1, 4, v236
	v_add_u32_e32 v8, 0x2000, v1
	v_lshrrev_b32_e32 v2, 7, v8
	s_movk_i32 s2, 0xe0
	v_and_b32_e32 v4, 32, v236
	v_and_or_b32 v3, v2, s2, v0
	v_bitop3_b32 v9, v1, v4, 48 bitop3:0x6c
	v_and_b32_e32 v10, 64, v236
	v_bfe_u32 v12, v236, 2, 4
	s_movk_i32 s2, 0xf0
	v_or_b32_e32 v1, v9, v10
	v_and_or_b32 v2, v2, s2, v12
	v_lshl_or_b32 v130, v2, 11, v1
	v_lshrrev_b32_e32 v2, 3, v236
	s_movk_i32 s2, 0x60
	v_and_or_b32 v0, v2, s2, v0
	s_movk_i32 s2, 0x70
	s_ashr_i32 s29, s9, 31
	v_lshl_or_b32 v132, v0, 11, v1
	v_and_or_b32 v0, v2, s2, v12
	s_lshr_b32 s2, s29, 29
	s_add_i32 s2, s9, s2
	s_lshr_b32 s8, s3, 6
	s_ashr_i32 s6, s2, 3
	s_and_b32 s2, s2, -8
	s_lshr_b32 s10, s3, 8
	s_lshl_b32 s28, s8, 10
	s_sub_i32 s2, s9, s2
	s_cmp_lt_i32 s2, 0
	s_movk_i32 s30, 0xbc
	s_cselect_b32 s7, s30, 0xbb
	s_mul_i32 s2, s2, s7
	s_add_i32 s2, s2, s6
	s_mul_hi_i32 s6, s2, 0x2e8ba2e9
	s_lshr_b32 s7, s6, 31
	s_ashr_i32 s6, s6, 5
	s_add_i32 s6, s6, s7
	s_lshl_b32 s9, s6, 3
	s_sub_i32 s7, 0x44, s9
	s_mulk_i32 s6, 0xb0
	s_min_u32 s11, s7, 8
	s_sub_i32 s12, s2, s6
	v_lshl_or_b32 v128, v3, 11, v1
	s_sext_i32_i16 s2, s12
	v_cvt_f32_ubyte0_e32 v3, s11
	v_cvt_f32_i32_e32 v2, s2
	v_rcp_iflag_f32_e32 v4, v3
	v_lshl_or_b32 v134, v0, 11, v1
	s_ashr_i32 s2, s2, 30
	s_or_b32 s2, s2, 1
	v_mul_f32_e32 v0, v2, v4
	v_trunc_f32_e32 v0, v0
	v_fma_f32 v1, -v0, v3, v2
	v_cvt_i32_f32_e32 v0, v0
	v_cmp_ge_f32_e64 s[6:7], |v1|, v3
	s_and_b64 s[6:7], s[6:7], exec
	s_cselect_b32 s2, s2, 0
	v_readfirstlane_b32 s6, v0
	s_add_i32 s2, s6, s2
	s_mul_i32 s6, s2, s11
	s_sub_i32 s6, s12, s6
	s_sext_i32_i16 s6, s6
	s_add_i32 s20, s9, s6
	s_sub_i32 s2, 21, s2
	s_ashr_i32 s21, s20, 31
	s_bfe_i64 s[12:13], s[2:3], 0x100000
	s_lshl_b64 s[6:7], s[20:21], 19
	s_lshl_b64 s[12:13], s[12:13], 19
	s_add_u32 s24, s4, s12
	s_addc_u32 s25, s5, s13
	s_add_i32 s21, s28, 0
	s_add_i32 m0, s21, 0x10000
	v_mov_b32_e32 v133, 0
	global_load_lds_dwordx4 v132, s[24:25]
	s_add_i32 m0, s21, 0x12000
	s_add_u32 s12, s24, 0x40000
	global_load_lds_dwordx4 v128, s[24:25]
	s_addc_u32 s13, s25, 0
	s_add_i32 m0, s21, 0x14000
	v_mov_b32_e32 v129, v133
	global_load_lds_dwordx4 v132, s[12:13]
	s_add_i32 m0, s21, 0x16000
	s_add_u32 s22, s92, s6
	s_addc_u32 s23, s93, s7
	s_add_i32 s31, s21, 0x2000
	global_load_lds_dwordx4 v128, s[12:13]
	s_mov_b32 m0, s21
	s_add_u32 s6, s22, 0x40000
	global_load_lds_dwordx4 v134, s[22:23]
	s_mov_b32 m0, s31
	s_addc_u32 s7, s23, 0
	s_add_i32 s33, s21, 0x4000
	global_load_lds_dwordx4 v130, s[22:23]
	s_mov_b32 m0, s33
	s_add_i32 s34, s21, 0x6000
	global_load_lds_dwordx4 v134, s[6:7]
	s_mov_b32 m0, s34
	v_mov_b32_e32 v135, v133
	global_load_lds_dwordx4 v130, s[6:7]
	v_mov_b32_e32 v131, v133
	s_cmp_eq_u32 s10, 1
	s_mov_b32 s35, 0
	v_lshl_add_u64 v[6:7], s[24:25], 0, v[132:133]
	v_lshl_add_u64 v[4:5], s[24:25], 0, v[128:129]
	v_lshl_add_u64 v[0:1], s[22:23], 0, v[134:135]
	s_cselect_b64 s[6:7], -1, 0
	s_cmp_lg_u32 s10, 1
	v_lshl_add_u64 v[2:3], s[22:23], 0, v[130:131]
	s_cbranch_scc1 .LBB0_1213
	s_barrier

.LBB0_1216:
	s_add_i32 s35, s35, 1
	s_mul_i32 s2, s35, s38
	s_mul_hi_u32 s3, s35, s39
	s_add_i32 s3, s3, s2
	s_mul_i32 s2, s35, s39
	v_readlane_b32 s13, v246, 46
	s_add_u32 s16, s2, s13
	s_addc_u32 s17, s3, s29
	v_cmp_gt_i64_e32 vcc, s[16:17], v[142:143]
	v_cmp_lt_i64_e64 s[2:3], s[16:17], v[140:141]
	s_cbranch_vccnz .LBB0_1218
	s_ashr_i32 s12, s16, 31
	s_lshr_b32 s12, s12, 29
	s_add_i32 s12, s16, s12
	s_ashr_i32 s13, s12, 3
	s_and_b32 s12, s12, -8
	s_sub_i32 s12, s16, s12
	s_cmp_lt_i32 s12, 0
	s_cselect_b32 s14, s30, 0xbb
	s_mul_i32 s12, s12, s14
	s_add_i32 s12, s12, s13
	s_mul_hi_i32 s13, s12, 0x2e8ba2e9
	s_lshr_b32 s14, s13, 31
	s_ashr_i32 s13, s13, 5
	s_add_i32 s13, s13, s14
	s_lshl_b32 s14, s13, 3
	s_sub_i32 s15, 0x44, s14
	s_min_i32 s15, s15, 8
	s_abs_i32 s16, s15
	v_cvt_f32_u32_e32 v0, s16
	s_sub_i32 s18, 0, s16
	s_mulk_i32 s13, 0xb0
	s_sub_i32 s13, s12, s13
	v_rcp_iflag_f32_e32 v0, v0
	s_abs_i32 s12, s13
	s_xor_b32 s17, s13, s15
	s_ashr_i32 s17, s17, 31
	v_mul_f32_e32 v0, 0x4f7ffffe, v0
	v_cvt_u32_f32_e32 v0, v0
	s_nop 0
	v_readfirstlane_b32 s19, v0
	s_mul_i32 s18, s18, s19
	s_mul_hi_u32 s18, s19, s18
	s_add_i32 s19, s19, s18
	s_mul_hi_u32 s18, s12, s19
	s_mul_i32 s19, s18, s16
	s_sub_i32 s12, s12, s19
	s_add_i32 s26, s18, 1
	s_sub_i32 s19, s12, s16
	s_cmp_ge_u32 s12, s16
	s_cselect_b32 s18, s26, s18
	s_cselect_b32 s12, s19, s12
	s_add_i32 s19, s18, 1
	s_cmp_ge_u32 s12, s16
	s_cselect_b32 s12, s19, s18
	s_xor_b32 s12, s12, s17
	s_sub_i32 s12, s12, s17
	s_mul_i32 s15, s12, s15
	s_sub_i32 s13, s13, s15
	s_add_i32 s14, s14, s13
	s_sub_i32 s12, 21, s12
